# FFN1: next tile's stage-0 LDS-DMA issued during the current tile's epilogue (LDS idle there), flag-skipped in the next prologue
# baseline (speedup 1.0000x reference)
; DI int TIDX() { int t = threadIdx.x; asm volatile("" : "+v"(t)); return t; }
; DI float sigmoidf_(float x) { return __builtin_amdgcn_rcpf(1.f + __expf(-x)); }
; DI void phase_ffn1(const P& p, int l, int hf, char* smem) {
;     ...
;     const int lane = TIDX() & 63, w = TIDX() >> 6, wm = w >> 1, wn = w & 1, hh = lane >> 5, c = lane & 31;
;     const int ml0 = m0 - mt0 * 128;
; #pragma unroll
;     for (int mi = 0; mi < 4; ++mi) {
;       const int rbase = ml0 + wm * 128 + mi * 32 + 4 * hh, n = c0 + wn * 32 + c;
; #pragma unroll
;       for (int i = 0; i < 16; ++i) {
;         const float g = acc[mi][0][i];
;         act[(size_t)EROW(rbase, i) * 2816 + n] = (h16)(g * sigmoidf_(g) * acc[mi][1][i]);
;       }
;     }
.LBB0_65:
	s_andn2_b64 vcc, exec, s[6:7]
	s_cbranch_vccnz .LBB0_84
	s_cmp_gt_i32 s68, 10
	s_mov_b64 s[6:7], -1
	s_cbranch_scc0 .LBB0_79
	s_and_b64 s[6:7], s[70:71], exec
	s_movk_i32 s6, 0x88
	s_cselect_b32 s20, s6, 0x80
	s_mov_b32 s10, s31
	s_lshr_b32 s21, s20, 3
	s_mov_b32 s6, s31
	s_ashr_i32 s22, s6, 3
	s_mul_i32 s23, s21, 44
	s_cmp_ge_i32 s22, s23
	s_cbranch_scc1 .LBB0_78
	s_add_u32 s6, s48, 0x12c0000
	s_addc_u32 s7, s49, 0
	s_add_u32 s24, s48, 0xf4ec000
	s_addc_u32 s25, s49, 0
	s_add_u32 s8, s48, 0x316c000
	s_addc_u32 s9, s49, 0
	s_and_b32 s38, s10, 7
	s_add_u32 s10, s48, 0x12c0040
	s_mul_i32 s38, s38, s21
	s_addc_u32 s11, s49, 0
	s_mov_b32 s39, 0
	s_branch .LBB0_71
.LBB0_69:
	v_mov_b32_e32 v0, v203
	v_mov_b32_e32 v130, v203
	s_barrier
	v_readlane_b32 s59, v252, 63
	s_add_i32 s40, s22, s59
	s_cmp_ge_i32 s40, s23
	s_cbranch_scc1 .Lf1pf_done
	s_mul_hi_i32 s50, s40, 0x2e8ba2e9
	s_lshr_b32 s51, s50, 31
	s_ashr_i32 s50, s50, 6
	s_add_i32 s50, s50, s51
	s_lshl_b32 s52, s50, 3
	s_sub_i32 s51, s21, s52
	s_min_i32 s53, s51, 8
	s_abs_i32 s51, s53
	v_cvt_f32_u32_e32 v134, s51
	s_sub_i32 s56, 0, s51
	s_mulk_i32 s50, 0xfea0
	s_add_i32 s50, s50, s40
	v_rcp_iflag_f32_e32 v134, v134
	s_abs_i32 s54, s50
	s_xor_b32 s55, s50, s53
	s_ashr_i32 s55, s55, 31
	v_mul_f32_e32 v134, 0x4f7ffffe, v134
	v_cvt_u32_f32_e32 v134, v134
	s_nop 0
	v_readfirstlane_b32 s57, v134
	s_mul_i32 s56, s56, s57
	s_mul_hi_u32 s56, s57, s56
	s_add_i32 s57, s57, s56
	s_mul_hi_u32 s56, s54, s57
	s_mul_i32 s57, s56, s51
	s_sub_i32 s54, s54, s57
	s_add_i32 s58, s56, 1
	s_sub_i32 s57, s54, s51
	s_cmp_ge_u32 s54, s51
	s_cselect_b32 s56, s58, s56
	s_cselect_b32 s54, s57, s54
	s_add_i32 s57, s56, 1
	s_cmp_ge_u32 s54, s51
	s_cselect_b32 s51, s57, s56
	s_xor_b32 s51, s51, s55
	s_sub_i32 s51, s51, s55
	s_add_i32 s52, s52, s38
	s_mul_i32 s53, s53, s51
	s_add_i32 s52, s52, s50
	s_sub_i32 s50, s52, s53
	s_cmp_ge_i32 s50, s20
	s_cbranch_scc1 .Lf1pf_done
	s_lshl_b32 s52, s50, 8
	s_ashr_i32 s53, s52, 31
	s_lshl_b64 s[52:53], s[52:53], 11
	s_add_u32 s42, s24, s52
	s_addc_u32 s43, s25, s53
	s_lshl_b32 s54, s51, 6
	s_sub_i32 s54, s54, s26
	s_ashr_i32 s55, s54, 31
	s_lshl_b64 s[54:55], s[54:55], 11
	s_add_u32 s44, s6, s54
	s_addc_u32 s45, s7, s55
	s_add_u32 m0, s18, 0x0
	s_nop 0
	global_load_lds_dwordx4 v139, s[42:43]
	s_add_u32 m0, s18, 0x1000
	s_nop 0
	global_load_lds_dwordx4 v140, s[42:43]
	s_add_u32 m0, s18, 0x2000
	s_nop 0
	global_load_lds_dwordx4 v141, s[42:43]
	s_add_u32 m0, s18, 0x3000
	s_nop 0
	global_load_lds_dwordx4 v142, s[42:43]
	s_add_u32 m0, s18, 0x4000
	s_nop 0
	global_load_lds_dwordx4 v143, s[44:45]
	s_add_u32 m0, s18, 0x5000
	s_nop 0
	global_load_lds_dwordx4 v144, s[44:45]
	s_mov_b32 s39, 1
.Lf1pf_done:
	s_movk_i32 s2, 0x1600
	v_and_b32_e32 v132, 0xffffff80, v130
	v_and_b32_e32 v131, 31, v0
	v_add_u32_e32 v132, s12, v132
	v_lshrrev_b32_e32 v0, 3, v0
	v_and_or_b32 v0, v0, 4, v132
	v_mul_f32_e32 v132, 0xbfb8aa3b, v114
	v_exp_f32_e32 v132, v132
	v_lshrrev_b32_e32 v130, 1, v130
	v_and_b32_e32 v130, 32, v130
	v_or3_b32 v130, v131, v130, s26
	v_add_f32_e32 v132, 1.0, v132
	v_rcp_f32_e32 v132, v132
	v_ashrrev_i32_e32 v131, 31, v130
	v_lshl_add_u64 v[130:131], v[130:131], 1, s[8:9]
	v_mul_f32_e32 v114, v114, v132
	v_fma_mixlo_f16 v98, v98, v114, 0
	v_mad_i64_i32 v[132:133], s[12:13], v0, s2, v[130:131]
	global_store_short v[132:133], v98, off
	v_mul_f32_e32 v98, 0xbfb8aa3b, v115
	v_exp_f32_e32 v98, v98
	s_nop 0
	v_add_f32_e32 v98, 1.0, v98
	v_rcp_f32_e32 v98, v98
	s_nop 0
	v_mul_f32_e32 v98, v115, v98
	v_fma_mixlo_f16 v114, v99, v98, 0
	v_or_b32_e32 v98, 1, v0
	v_mad_i64_i32 v[98:99], s[12:13], v98, s2, v[130:131]
	global_store_short v[98:99], v114, off
	v_mul_f32_e32 v98, 0xbfb8aa3b, v116
	v_exp_f32_e32 v98, v98
	s_nop 0
	v_add_f32_e32 v98, 1.0, v98
	v_rcp_f32_e32 v98, v98
	s_nop 0
	v_mul_f32_e32 v98, v116, v98
	v_fma_mixlo_f16 v100, v100, v98, 0
	v_or_b32_e32 v98, 2, v0
	v_mad_i64_i32 v[98:99], s[12:13], v98, s2, v[130:131]
	global_store_short v[98:99], v100, off
	v_mul_f32_e32 v98, 0xbfb8aa3b, v117
	v_exp_f32_e32 v98, v98
	s_nop 0
	v_add_f32_e32 v98, 1.0, v98
	v_rcp_f32_e32 v98, v98
	s_nop 0
	v_mul_f32_e32 v98, v117, v98
	v_fma_mixlo_f16 v100, v101, v98, 0
	v_or_b32_e32 v98, 3, v0
	v_mad_i64_i32 v[98:99], s[12:13], v98, s2, v[130:131]
	global_store_short v[98:99], v100, off
	v_mul_f32_e32 v98, 0xbfb8aa3b, v118
	v_exp_f32_e32 v98, v98
	s_nop 0
	v_add_f32_e32 v98, 1.0, v98
	v_rcp_f32_e32 v98, v98
	s_nop 0
	v_mul_f32_e32 v98, v118, v98
	v_fma_mixlo_f16 v100, v102, v98, 0
	v_or_b32_e32 v98, 8, v0
	v_mad_i64_i32 v[98:99], s[12:13], v98, s2, v[130:131]
	global_store_short v[98:99], v100, off
	v_mul_f32_e32 v98, 0xbfb8aa3b, v119
	v_exp_f32_e32 v98, v98
	s_nop 0
	v_add_f32_e32 v98, 1.0, v98
	v_rcp_f32_e32 v98, v98
	s_nop 0
	v_mul_f32_e32 v98, v119, v98
	v_fma_mixlo_f16 v100, v103, v98, 0
	v_or_b32_e32 v98, 9, v0
	v_mad_i64_i32 v[98:99], s[12:13], v98, s2, v[130:131]
	global_store_short v[98:99], v100, off
	v_mul_f32_e32 v98, 0xbfb8aa3b, v120
	v_exp_f32_e32 v98, v98
	s_nop 0
	v_add_f32_e32 v98, 1.0, v98
	v_rcp_f32_e32 v98, v98
	s_nop 0
	v_mul_f32_e32 v98, v120, v98
	v_fma_mixlo_f16 v100, v104, v98, 0
	v_or_b32_e32 v98, 10, v0
	v_mad_i64_i32 v[98:99], s[12:13], v98, s2, v[130:131]
	global_store_short v[98:99], v100, off
	v_mul_f32_e32 v98, 0xbfb8aa3b, v121
	v_exp_f32_e32 v98, v98
	s_nop 0
	v_add_f32_e32 v98, 1.0, v98
	v_rcp_f32_e32 v98, v98
	s_nop 0
	v_mul_f32_e32 v98, v121, v98
	v_fma_mixlo_f16 v100, v105, v98, 0
	v_or_b32_e32 v98, 11, v0
	v_mad_i64_i32 v[98:99], s[12:13], v98, s2, v[130:131]
	global_store_short v[98:99], v100, off
	v_mul_f32_e32 v98, 0xbfb8aa3b, v122
	v_exp_f32_e32 v98, v98
; DI float sigmoidf_(float x) { return __builtin_amdgcn_rcpf(1.f + __expf(-x)); }
; DI void phase_ffn1(const P& p, int l, int hf, char* smem) {
;     ...
; #pragma unroll
;     for (int mi = 0; mi < 4; ++mi) {
;       const int rbase = ml0 + wm * 128 + mi * 32 + 4 * hh, n = c0 + wn * 32 + c;
; #pragma unroll
;       for (int i = 0; i < 16; ++i) {
;         const float g = acc[mi][0][i];
;         act[(size_t)EROW(rbase, i) * 2816 + n] = (h16)(g * sigmoidf_(g) * acc[mi][1][i]);
;       }
;     }
	s_nop 0
	v_add_f32_e32 v98, 1.0, v98
	v_rcp_f32_e32 v98, v98
	s_nop 0
	v_mul_f32_e32 v98, v122, v98
	v_fma_mixlo_f16 v100, v106, v98, 0
	v_or_b32_e32 v98, 16, v0
	v_mad_i64_i32 v[98:99], s[12:13], v98, s2, v[130:131]
	global_store_short v[98:99], v100, off
	v_mul_f32_e32 v98, 0xbfb8aa3b, v123
	v_exp_f32_e32 v98, v98
	s_nop 0
	v_add_f32_e32 v98, 1.0, v98
	v_rcp_f32_e32 v98, v98
	s_nop 0
	v_mul_f32_e32 v98, v123, v98
	v_fma_mixlo_f16 v100, v107, v98, 0
	v_or_b32_e32 v98, 17, v0
	v_mad_i64_i32 v[98:99], s[12:13], v98, s2, v[130:131]
	global_store_short v[98:99], v100, off
	v_mul_f32_e32 v98, 0xbfb8aa3b, v124
	v_exp_f32_e32 v98, v98
	s_nop 0
	v_add_f32_e32 v98, 1.0, v98
	v_rcp_f32_e32 v98, v98
	s_nop 0
	v_mul_f32_e32 v98, v124, v98
	v_fma_mixlo_f16 v100, v108, v98, 0
	v_or_b32_e32 v98, 18, v0
	v_mad_i64_i32 v[98:99], s[12:13], v98, s2, v[130:131]
	global_store_short v[98:99], v100, off
	v_mul_f32_e32 v98, 0xbfb8aa3b, v125
	v_exp_f32_e32 v98, v98
	s_nop 0
	v_add_f32_e32 v98, 1.0, v98
	v_rcp_f32_e32 v98, v98
	s_nop 0
	v_mul_f32_e32 v98, v125, v98
	v_fma_mixlo_f16 v100, v109, v98, 0
	v_or_b32_e32 v98, 19, v0
	v_mad_i64_i32 v[98:99], s[12:13], v98, s2, v[130:131]
	global_store_short v[98:99], v100, off
	v_mul_f32_e32 v98, 0xbfb8aa3b, v126
	v_exp_f32_e32 v98, v98
	s_nop 0
	v_add_f32_e32 v98, 1.0, v98
	v_rcp_f32_e32 v98, v98
	s_nop 0
	v_mul_f32_e32 v98, v126, v98
	v_fma_mixlo_f16 v100, v110, v98, 0
	v_or_b32_e32 v98, 24, v0
	v_mad_i64_i32 v[98:99], s[12:13], v98, s2, v[130:131]
	global_store_short v[98:99], v100, off
	v_mul_f32_e32 v98, 0xbfb8aa3b, v127
	v_exp_f32_e32 v98, v98
	s_nop 0
	v_add_f32_e32 v98, 1.0, v98
	v_rcp_f32_e32 v98, v98
	s_nop 0
	v_mul_f32_e32 v98, v127, v98
	v_fma_mixlo_f16 v100, v111, v98, 0
	v_or_b32_e32 v98, 25, v0
	v_mad_i64_i32 v[98:99], s[12:13], v98, s2, v[130:131]
	global_store_short v[98:99], v100, off
	v_mul_f32_e32 v98, 0xbfb8aa3b, v128
	v_exp_f32_e32 v98, v98
	s_nop 0
	v_add_f32_e32 v98, 1.0, v98
	v_rcp_f32_e32 v98, v98
	s_nop 0
	v_mul_f32_e32 v98, v128, v98
	v_fma_mixlo_f16 v100, v112, v98, 0
	v_or_b32_e32 v98, 26, v0
	v_mad_i64_i32 v[98:99], s[12:13], v98, s2, v[130:131]
	global_store_short v[98:99], v100, off
	v_mul_f32_e32 v98, 0xbfb8aa3b, v129
	v_exp_f32_e32 v98, v98
	s_nop 0
	v_add_f32_e32 v98, 1.0, v98
	v_rcp_f32_e32 v98, v98
	s_nop 0
	v_mul_f32_e32 v98, v129, v98
	v_fma_mixlo_f16 v100, v113, v98, 0
	v_or_b32_e32 v98, 27, v0
	v_mad_i64_i32 v[98:99], s[12:13], v98, s2, v[130:131]
	global_store_short v[98:99], v100, off
	v_mul_f32_e32 v99, 0xbfb8aa3b, v82
	v_exp_f32_e32 v99, v99
	v_or_b32_e32 v98, 32, v0
	v_add_f32_e32 v99, 1.0, v99
	v_rcp_f32_e32 v99, v99
	s_nop 0
	v_mul_f32_e32 v82, v82, v99
	v_fma_mixlo_f16 v66, v66, v82, 0
	v_mad_i64_i32 v[98:99], s[12:13], v98, s2, v[130:131]
	global_store_short v[98:99], v66, off
	v_mul_f32_e32 v66, 0xbfb8aa3b, v83
	v_exp_f32_e32 v66, v66
	s_nop 0
	v_add_f32_e32 v66, 1.0, v66
	v_rcp_f32_e32 v66, v66
	s_nop 0
	v_mul_f32_e32 v66, v83, v66
	v_fma_mixlo_f16 v82, v67, v66, 0
	v_or_b32_e32 v66, 33, v0
	v_mad_i64_i32 v[66:67], s[12:13], v66, s2, v[130:131]
	global_store_short v[66:67], v82, off
	v_mul_f32_e32 v66, 0xbfb8aa3b, v84
	v_exp_f32_e32 v66, v66
	s_nop 0
	v_add_f32_e32 v66, 1.0, v66
	v_rcp_f32_e32 v66, v66
	s_nop 0
	v_mul_f32_e32 v66, v84, v66
	v_fma_mixlo_f16 v68, v68, v66, 0
	v_or_b32_e32 v66, 34, v0
	v_mad_i64_i32 v[66:67], s[12:13], v66, s2, v[130:131]
	global_store_short v[66:67], v68, off
	v_mul_f32_e32 v66, 0xbfb8aa3b, v85
	v_exp_f32_e32 v66, v66
	s_nop 0
	v_add_f32_e32 v66, 1.0, v66
	v_rcp_f32_e32 v66, v66
	s_nop 0
	v_mul_f32_e32 v66, v85, v66
	v_fma_mixlo_f16 v68, v69, v66, 0
	v_or_b32_e32 v66, 35, v0
	v_mad_i64_i32 v[66:67], s[12:13], v66, s2, v[130:131]
	global_store_short v[66:67], v68, off
	v_mul_f32_e32 v66, 0xbfb8aa3b, v86
	v_exp_f32_e32 v66, v66
	s_nop 0
	v_add_f32_e32 v66, 1.0, v66
	v_rcp_f32_e32 v66, v66
	s_nop 0
	v_mul_f32_e32 v66, v86, v66
	v_fma_mixlo_f16 v68, v70, v66, 0
	v_or_b32_e32 v66, 40, v0
	v_mad_i64_i32 v[66:67], s[12:13], v66, s2, v[130:131]
	global_store_short v[66:67], v68, off
	v_mul_f32_e32 v66, 0xbfb8aa3b, v87
	v_exp_f32_e32 v66, v66
	s_nop 0
	v_add_f32_e32 v66, 1.0, v66
	v_rcp_f32_e32 v66, v66
	s_nop 0
	v_mul_f32_e32 v66, v87, v66
	v_fma_mixlo_f16 v68, v71, v66, 0
	v_or_b32_e32 v66, 41, v0
	v_mad_i64_i32 v[66:67], s[12:13], v66, s2, v[130:131]
	global_store_short v[66:67], v68, off
	v_mul_f32_e32 v66, 0xbfb8aa3b, v88
	v_exp_f32_e32 v66, v66
	s_nop 0
	v_add_f32_e32 v66, 1.0, v66
	v_rcp_f32_e32 v66, v66
	s_nop 0
	v_mul_f32_e32 v66, v88, v66
	v_fma_mixlo_f16 v68, v72, v66, 0
	v_or_b32_e32 v66, 42, v0
	v_mad_i64_i32 v[66:67], s[12:13], v66, s2, v[130:131]
	global_store_short v[66:67], v68, off
	v_mul_f32_e32 v66, 0xbfb8aa3b, v89
	v_exp_f32_e32 v66, v66
	s_nop 0
	v_add_f32_e32 v66, 1.0, v66
	v_rcp_f32_e32 v66, v66
	s_nop 0
	v_mul_f32_e32 v66, v89, v66
	v_fma_mixlo_f16 v68, v73, v66, 0
	v_or_b32_e32 v66, 43, v0
	v_mad_i64_i32 v[66:67], s[12:13], v66, s2, v[130:131]
	global_store_short v[66:67], v68, off
	v_mul_f32_e32 v66, 0xbfb8aa3b, v90
	v_exp_f32_e32 v66, v66
	s_nop 0
	v_add_f32_e32 v66, 1.0, v66
	v_rcp_f32_e32 v66, v66
	s_nop 0
	v_mul_f32_e32 v66, v90, v66
	v_fma_mixlo_f16 v68, v74, v66, 0
	v_or_b32_e32 v66, 48, v0
	v_mad_i64_i32 v[66:67], s[12:13], v66, s2, v[130:131]
	global_store_short v[66:67], v68, off
	v_mul_f32_e32 v66, 0xbfb8aa3b, v91
	v_exp_f32_e32 v66, v66
	s_nop 0
	v_add_f32_e32 v66, 1.0, v66
	v_rcp_f32_e32 v66, v66
	s_nop 0
	v_mul_f32_e32 v66, v91, v66
	v_fma_mixlo_f16 v68, v75, v66, 0
	v_or_b32_e32 v66, 49, v0
	v_mad_i64_i32 v[66:67], s[12:13], v66, s2, v[130:131]
	global_store_short v[66:67], v68, off
; DI float sigmoidf_(float x) { return __builtin_amdgcn_rcpf(1.f + __expf(-x)); }
; DI void phase_ffn1(const P& p, int l, int hf, char* smem) {
;     ...
; #pragma unroll
;     for (int mi = 0; mi < 4; ++mi) {
;       const int rbase = ml0 + wm * 128 + mi * 32 + 4 * hh, n = c0 + wn * 32 + c;
; #pragma unroll
;       for (int i = 0; i < 16; ++i) {
;         const float g = acc[mi][0][i];
;         act[(size_t)EROW(rbase, i) * 2816 + n] = (h16)(g * sigmoidf_(g) * acc[mi][1][i]);
;       }
;     }
	v_mul_f32_e32 v66, 0xbfb8aa3b, v92
	v_exp_f32_e32 v66, v66
	s_nop 0
	v_add_f32_e32 v66, 1.0, v66
	v_rcp_f32_e32 v66, v66
	s_nop 0
	v_mul_f32_e32 v66, v92, v66
	v_fma_mixlo_f16 v68, v76, v66, 0
	v_or_b32_e32 v66, 50, v0
	v_mad_i64_i32 v[66:67], s[12:13], v66, s2, v[130:131]
	global_store_short v[66:67], v68, off
	v_mul_f32_e32 v66, 0xbfb8aa3b, v93
	v_exp_f32_e32 v66, v66
	s_nop 0
	v_add_f32_e32 v66, 1.0, v66
	v_rcp_f32_e32 v66, v66
	s_nop 0
	v_mul_f32_e32 v66, v93, v66
	v_fma_mixlo_f16 v68, v77, v66, 0
	v_or_b32_e32 v66, 51, v0
	v_mad_i64_i32 v[66:67], s[12:13], v66, s2, v[130:131]
	global_store_short v[66:67], v68, off
	v_mul_f32_e32 v66, 0xbfb8aa3b, v94
	v_exp_f32_e32 v66, v66
	s_nop 0
	v_add_f32_e32 v66, 1.0, v66
	v_rcp_f32_e32 v66, v66
	s_nop 0
	v_mul_f32_e32 v66, v94, v66
	v_fma_mixlo_f16 v68, v78, v66, 0
	v_or_b32_e32 v66, 56, v0
	v_mad_i64_i32 v[66:67], s[12:13], v66, s2, v[130:131]
	global_store_short v[66:67], v68, off
	v_mul_f32_e32 v66, 0xbfb8aa3b, v95
	v_exp_f32_e32 v66, v66
	s_nop 0
	v_add_f32_e32 v66, 1.0, v66
	v_rcp_f32_e32 v66, v66
	s_nop 0
	v_mul_f32_e32 v66, v95, v66
	v_fma_mixlo_f16 v68, v79, v66, 0
	v_or_b32_e32 v66, 57, v0
	v_mad_i64_i32 v[66:67], s[12:13], v66, s2, v[130:131]
	global_store_short v[66:67], v68, off
	v_mul_f32_e32 v66, 0xbfb8aa3b, v96
	v_exp_f32_e32 v66, v66
	s_nop 0
	v_add_f32_e32 v66, 1.0, v66
	v_rcp_f32_e32 v66, v66
	s_nop 0
	v_mul_f32_e32 v66, v96, v66
	v_fma_mixlo_f16 v68, v80, v66, 0
	v_or_b32_e32 v66, 58, v0
	v_mad_i64_i32 v[66:67], s[12:13], v66, s2, v[130:131]
	global_store_short v[66:67], v68, off
	v_mul_f32_e32 v66, 0xbfb8aa3b, v97
	v_exp_f32_e32 v66, v66
	s_nop 0
	v_add_f32_e32 v66, 1.0, v66
	v_rcp_f32_e32 v66, v66
	s_nop 0
	v_mul_f32_e32 v66, v97, v66
	v_fma_mixlo_f16 v68, v81, v66, 0
	v_or_b32_e32 v66, 59, v0
	v_mad_i64_i32 v[66:67], s[12:13], v66, s2, v[130:131]
	global_store_short v[66:67], v68, off
	v_mul_f32_e32 v67, 0xbfb8aa3b, v50
	v_exp_f32_e32 v67, v67
	v_or_b32_e32 v66, 64, v0
	v_add_f32_e32 v67, 1.0, v67
	v_rcp_f32_e32 v67, v67
	s_nop 0
	v_mul_f32_e32 v50, v50, v67
	v_fma_mixlo_f16 v34, v34, v50, 0
	v_mad_i64_i32 v[66:67], s[12:13], v66, s2, v[130:131]
	global_store_short v[66:67], v34, off
	v_mul_f32_e32 v34, 0xbfb8aa3b, v51
	v_exp_f32_e32 v34, v34
	s_nop 0
	v_add_f32_e32 v34, 1.0, v34
	v_rcp_f32_e32 v34, v34
	s_nop 0
	v_mul_f32_e32 v34, v51, v34
	v_fma_mixlo_f16 v50, v35, v34, 0
	v_or_b32_e32 v34, 0x41, v0
	v_mad_i64_i32 v[34:35], s[12:13], v34, s2, v[130:131]
	global_store_short v[34:35], v50, off
	v_mul_f32_e32 v34, 0xbfb8aa3b, v52
	v_exp_f32_e32 v34, v34
	s_nop 0
	v_add_f32_e32 v34, 1.0, v34
	v_rcp_f32_e32 v34, v34
	s_nop 0
	v_mul_f32_e32 v34, v52, v34
	v_fma_mixlo_f16 v36, v36, v34, 0
	v_or_b32_e32 v34, 0x42, v0
	v_mad_i64_i32 v[34:35], s[12:13], v34, s2, v[130:131]
	global_store_short v[34:35], v36, off
	v_mul_f32_e32 v34, 0xbfb8aa3b, v53
	v_exp_f32_e32 v34, v34
	s_nop 0
	v_add_f32_e32 v34, 1.0, v34
	v_rcp_f32_e32 v34, v34
	s_nop 0
	v_mul_f32_e32 v34, v53, v34
	v_fma_mixlo_f16 v36, v37, v34, 0
	v_or_b32_e32 v34, 0x43, v0
	v_mad_i64_i32 v[34:35], s[12:13], v34, s2, v[130:131]
	global_store_short v[34:35], v36, off
	v_mul_f32_e32 v34, 0xbfb8aa3b, v54
	v_exp_f32_e32 v34, v34
	s_nop 0
	v_add_f32_e32 v34, 1.0, v34
	v_rcp_f32_e32 v34, v34
	s_nop 0
	v_mul_f32_e32 v34, v54, v34
	v_fma_mixlo_f16 v36, v38, v34, 0
	v_or_b32_e32 v34, 0x48, v0
	v_mad_i64_i32 v[34:35], s[12:13], v34, s2, v[130:131]
	global_store_short v[34:35], v36, off
	v_mul_f32_e32 v34, 0xbfb8aa3b, v55
	v_exp_f32_e32 v34, v34
	s_nop 0
	v_add_f32_e32 v34, 1.0, v34
	v_rcp_f32_e32 v34, v34
	s_nop 0
	v_mul_f32_e32 v34, v55, v34
	v_fma_mixlo_f16 v36, v39, v34, 0
	v_or_b32_e32 v34, 0x49, v0
	v_mad_i64_i32 v[34:35], s[12:13], v34, s2, v[130:131]
	global_store_short v[34:35], v36, off
	v_mul_f32_e32 v34, 0xbfb8aa3b, v56
	v_exp_f32_e32 v34, v34
	s_nop 0
	v_add_f32_e32 v34, 1.0, v34
	v_rcp_f32_e32 v34, v34
	s_nop 0
	v_mul_f32_e32 v34, v56, v34
	v_fma_mixlo_f16 v36, v40, v34, 0
	v_or_b32_e32 v34, 0x4a, v0
	v_mad_i64_i32 v[34:35], s[12:13], v34, s2, v[130:131]
	global_store_short v[34:35], v36, off
	v_mul_f32_e32 v34, 0xbfb8aa3b, v57
	v_exp_f32_e32 v34, v34
	s_nop 0
	v_add_f32_e32 v34, 1.0, v34
	v_rcp_f32_e32 v34, v34
	s_nop 0
	v_mul_f32_e32 v34, v57, v34
	v_fma_mixlo_f16 v36, v41, v34, 0
	v_or_b32_e32 v34, 0x4b, v0
	v_mad_i64_i32 v[34:35], s[12:13], v34, s2, v[130:131]
	global_store_short v[34:35], v36, off
	v_mul_f32_e32 v34, 0xbfb8aa3b, v58
	v_exp_f32_e32 v34, v34
	s_nop 0
	v_add_f32_e32 v34, 1.0, v34
	v_rcp_f32_e32 v34, v34
	s_nop 0
	v_mul_f32_e32 v34, v58, v34
	v_fma_mixlo_f16 v36, v42, v34, 0
	v_or_b32_e32 v34, 0x50, v0
	v_mad_i64_i32 v[34:35], s[12:13], v34, s2, v[130:131]
	global_store_short v[34:35], v36, off
	v_mul_f32_e32 v34, 0xbfb8aa3b, v59
	v_exp_f32_e32 v34, v34
	s_nop 0
	v_add_f32_e32 v34, 1.0, v34
	v_rcp_f32_e32 v34, v34
	s_nop 0
	v_mul_f32_e32 v34, v59, v34
	v_fma_mixlo_f16 v36, v43, v34, 0
	v_or_b32_e32 v34, 0x51, v0
	v_mad_i64_i32 v[34:35], s[12:13], v34, s2, v[130:131]
	global_store_short v[34:35], v36, off
	v_mul_f32_e32 v34, 0xbfb8aa3b, v60
	v_exp_f32_e32 v34, v34
	s_nop 0
	v_add_f32_e32 v34, 1.0, v34
	v_rcp_f32_e32 v34, v34
	s_nop 0
	v_mul_f32_e32 v34, v60, v34
	v_fma_mixlo_f16 v36, v44, v34, 0
	v_or_b32_e32 v34, 0x52, v0
	v_mad_i64_i32 v[34:35], s[12:13], v34, s2, v[130:131]
	global_store_short v[34:35], v36, off
	v_mul_f32_e32 v34, 0xbfb8aa3b, v61
	v_exp_f32_e32 v34, v34
	s_nop 0
	v_add_f32_e32 v34, 1.0, v34
	v_rcp_f32_e32 v34, v34
	s_nop 0
	v_mul_f32_e32 v34, v61, v34
	v_fma_mixlo_f16 v36, v45, v34, 0
	v_or_b32_e32 v34, 0x53, v0
	v_mad_i64_i32 v[34:35], s[12:13], v34, s2, v[130:131]
; DI float sigmoidf_(float x) { return __builtin_amdgcn_rcpf(1.f + __expf(-x)); }
; DI void phase_ffn1(const P& p, int l, int hf, char* smem) {
;     ...
;     for (int mi = 0; mi < 4; ++mi) {
;       const int rbase = ml0 + wm * 128 + mi * 32 + 4 * hh, n = c0 + wn * 32 + c;
; #pragma unroll
;       for (int i = 0; i < 16; ++i) {
;         const float g = acc[mi][0][i];
;         act[(size_t)EROW(rbase, i) * 2816 + n] = (h16)(g * sigmoidf_(g) * acc[mi][1][i]);
;       }
;     }
	global_store_short v[34:35], v36, off
	v_mul_f32_e32 v34, 0xbfb8aa3b, v62
	v_exp_f32_e32 v34, v34
	s_nop 0
	v_add_f32_e32 v34, 1.0, v34
	v_rcp_f32_e32 v34, v34
	s_nop 0
	v_mul_f32_e32 v34, v62, v34
	v_fma_mixlo_f16 v36, v46, v34, 0
	v_or_b32_e32 v34, 0x58, v0
	v_mad_i64_i32 v[34:35], s[12:13], v34, s2, v[130:131]
	global_store_short v[34:35], v36, off
	v_mul_f32_e32 v34, 0xbfb8aa3b, v63
	v_exp_f32_e32 v34, v34
	s_nop 0
	v_add_f32_e32 v34, 1.0, v34
	v_rcp_f32_e32 v34, v34
	s_nop 0
	v_mul_f32_e32 v34, v63, v34
	v_fma_mixlo_f16 v36, v47, v34, 0
	v_or_b32_e32 v34, 0x59, v0
	v_mad_i64_i32 v[34:35], s[12:13], v34, s2, v[130:131]
	global_store_short v[34:35], v36, off
	v_mul_f32_e32 v34, 0xbfb8aa3b, v64
	v_exp_f32_e32 v34, v34
	s_nop 0
	v_add_f32_e32 v34, 1.0, v34
	v_rcp_f32_e32 v34, v34
	s_nop 0
	v_mul_f32_e32 v34, v64, v34
	v_fma_mixlo_f16 v36, v48, v34, 0
	v_or_b32_e32 v34, 0x5a, v0
	v_mad_i64_i32 v[34:35], s[12:13], v34, s2, v[130:131]
	global_store_short v[34:35], v36, off
	v_mul_f32_e32 v34, 0xbfb8aa3b, v65
	v_exp_f32_e32 v34, v34
	s_nop 0
	v_add_f32_e32 v34, 1.0, v34
	v_rcp_f32_e32 v34, v34
	s_nop 0
	v_mul_f32_e32 v34, v65, v34
	v_fma_mixlo_f16 v36, v49, v34, 0
	v_or_b32_e32 v34, 0x5b, v0
	v_mad_i64_i32 v[34:35], s[12:13], v34, s2, v[130:131]
	global_store_short v[34:35], v36, off
	v_mul_f32_e32 v35, 0xbfb8aa3b, v18
	v_exp_f32_e32 v35, v35
	v_or_b32_e32 v34, 0x60, v0
	v_add_f32_e32 v35, 1.0, v35
	v_rcp_f32_e32 v35, v35
	s_nop 0
	v_mul_f32_e32 v18, v18, v35
	v_fma_mixlo_f16 v2, v2, v18, 0
	v_mad_i64_i32 v[34:35], s[12:13], v34, s2, v[130:131]
	global_store_short v[34:35], v2, off
	v_mul_f32_e32 v2, 0xbfb8aa3b, v19
	v_exp_f32_e32 v2, v2
	s_nop 0
	v_add_f32_e32 v2, 1.0, v2
	v_rcp_f32_e32 v2, v2
	s_nop 0
	v_mul_f32_e32 v2, v19, v2
	v_fma_mixlo_f16 v18, v3, v2, 0
	v_or_b32_e32 v2, 0x61, v0
	v_mad_i64_i32 v[2:3], s[12:13], v2, s2, v[130:131]
	global_store_short v[2:3], v18, off
	v_mul_f32_e32 v2, 0xbfb8aa3b, v20
	v_exp_f32_e32 v2, v2
	s_nop 0
	v_add_f32_e32 v2, 1.0, v2
	v_rcp_f32_e32 v2, v2
	s_nop 0
	v_mul_f32_e32 v2, v20, v2
	v_fma_mixlo_f16 v4, v4, v2, 0
	v_or_b32_e32 v2, 0x62, v0
	v_mad_i64_i32 v[2:3], s[12:13], v2, s2, v[130:131]
	global_store_short v[2:3], v4, off
	v_mul_f32_e32 v2, 0xbfb8aa3b, v21
	v_exp_f32_e32 v2, v2
	s_nop 0
	v_add_f32_e32 v2, 1.0, v2
	v_rcp_f32_e32 v2, v2
	s_nop 0
	v_mul_f32_e32 v2, v21, v2
	v_fma_mixlo_f16 v4, v5, v2, 0
	v_or_b32_e32 v2, 0x63, v0
	v_mad_i64_i32 v[2:3], s[12:13], v2, s2, v[130:131]
	global_store_short v[2:3], v4, off
	v_mul_f32_e32 v2, 0xbfb8aa3b, v22
	v_exp_f32_e32 v2, v2
	s_nop 0
	v_add_f32_e32 v2, 1.0, v2
	v_rcp_f32_e32 v2, v2
	s_nop 0
	v_mul_f32_e32 v2, v22, v2
	v_fma_mixlo_f16 v4, v6, v2, 0
	v_or_b32_e32 v2, 0x68, v0
	v_mad_i64_i32 v[2:3], s[12:13], v2, s2, v[130:131]
	global_store_short v[2:3], v4, off
	v_mul_f32_e32 v2, 0xbfb8aa3b, v23
	v_exp_f32_e32 v2, v2
	s_nop 0
	v_add_f32_e32 v2, 1.0, v2
	v_rcp_f32_e32 v2, v2
	s_nop 0
	v_mul_f32_e32 v2, v23, v2
	v_fma_mixlo_f16 v4, v7, v2, 0
	v_or_b32_e32 v2, 0x69, v0
	v_mad_i64_i32 v[2:3], s[12:13], v2, s2, v[130:131]
	global_store_short v[2:3], v4, off
	v_mul_f32_e32 v2, 0xbfb8aa3b, v24
	v_exp_f32_e32 v2, v2
	s_nop 0
	v_add_f32_e32 v2, 1.0, v2
	v_rcp_f32_e32 v2, v2
	s_nop 0
	v_mul_f32_e32 v2, v24, v2
	v_fma_mixlo_f16 v4, v8, v2, 0
	v_or_b32_e32 v2, 0x6a, v0
	v_mad_i64_i32 v[2:3], s[12:13], v2, s2, v[130:131]
	global_store_short v[2:3], v4, off
	v_mul_f32_e32 v2, 0xbfb8aa3b, v25
	v_exp_f32_e32 v2, v2
	s_nop 0
	v_add_f32_e32 v2, 1.0, v2
	v_rcp_f32_e32 v2, v2
	s_nop 0
	v_mul_f32_e32 v2, v25, v2
	v_fma_mixlo_f16 v4, v9, v2, 0
	v_or_b32_e32 v2, 0x6b, v0
	v_mad_i64_i32 v[2:3], s[12:13], v2, s2, v[130:131]
	global_store_short v[2:3], v4, off
	v_mul_f32_e32 v2, 0xbfb8aa3b, v26
	v_exp_f32_e32 v2, v2
	s_nop 0
	v_add_f32_e32 v2, 1.0, v2
	v_rcp_f32_e32 v2, v2
	s_nop 0
	v_mul_f32_e32 v2, v26, v2
	v_fma_mixlo_f16 v4, v10, v2, 0
	v_or_b32_e32 v2, 0x70, v0
	v_mad_i64_i32 v[2:3], s[12:13], v2, s2, v[130:131]
	global_store_short v[2:3], v4, off
	v_mul_f32_e32 v2, 0xbfb8aa3b, v27
	v_exp_f32_e32 v2, v2
	s_nop 0
	v_add_f32_e32 v2, 1.0, v2
	v_rcp_f32_e32 v2, v2
	s_nop 0
	v_mul_f32_e32 v2, v27, v2
	v_fma_mixlo_f16 v4, v11, v2, 0
	v_or_b32_e32 v2, 0x71, v0
	v_mad_i64_i32 v[2:3], s[12:13], v2, s2, v[130:131]
	global_store_short v[2:3], v4, off
	v_mul_f32_e32 v2, 0xbfb8aa3b, v28
	v_exp_f32_e32 v2, v2
	s_nop 0
	v_add_f32_e32 v2, 1.0, v2
	v_rcp_f32_e32 v2, v2
	s_nop 0
	v_mul_f32_e32 v2, v28, v2
	v_fma_mixlo_f16 v4, v12, v2, 0
	v_or_b32_e32 v2, 0x72, v0
	v_mad_i64_i32 v[2:3], s[12:13], v2, s2, v[130:131]
	global_store_short v[2:3], v4, off
	v_mul_f32_e32 v2, 0xbfb8aa3b, v29
	v_exp_f32_e32 v2, v2
	s_nop 0
	v_add_f32_e32 v2, 1.0, v2
	v_rcp_f32_e32 v2, v2
	s_nop 0
	v_mul_f32_e32 v2, v29, v2
	v_fma_mixlo_f16 v4, v13, v2, 0
	v_or_b32_e32 v2, 0x73, v0
	v_mad_i64_i32 v[2:3], s[12:13], v2, s2, v[130:131]
	global_store_short v[2:3], v4, off
	v_mul_f32_e32 v2, 0xbfb8aa3b, v30
	v_exp_f32_e32 v2, v2
	s_nop 0
	v_add_f32_e32 v2, 1.0, v2
	v_rcp_f32_e32 v2, v2
	s_nop 0
	v_mul_f32_e32 v2, v30, v2
	v_fma_mixlo_f16 v4, v14, v2, 0
	v_or_b32_e32 v2, 0x78, v0
	v_mad_i64_i32 v[2:3], s[12:13], v2, s2, v[130:131]
	global_store_short v[2:3], v4, off
	v_mul_f32_e32 v2, 0xbfb8aa3b, v31
	v_exp_f32_e32 v2, v2
	s_nop 0
	v_add_f32_e32 v2, 1.0, v2
	v_rcp_f32_e32 v2, v2
	s_nop 0
	v_mul_f32_e32 v2, v31, v2
	v_fma_mixlo_f16 v4, v15, v2, 0
	v_or_b32_e32 v2, 0x79, v0
	v_mad_i64_i32 v[2:3], s[12:13], v2, s2, v[130:131]
	global_store_short v[2:3], v4, off
	v_mul_f32_e32 v2, 0xbfb8aa3b, v32
	v_exp_f32_e32 v2, v2
	s_nop 0
	v_add_f32_e32 v2, 1.0, v2
	v_rcp_f32_e32 v2, v2
	s_nop 0
	v_mul_f32_e32 v2, v32, v2
	v_fma_mixlo_f16 v4, v16, v2, 0
	v_or_b32_e32 v2, 0x7a, v0
	v_mad_i64_i32 v[2:3], s[12:13], v2, s2, v[130:131]
	global_store_short v[2:3], v4, off
	v_mul_f32_e32 v2, 0xbfb8aa3b, v33
	v_exp_f32_e32 v2, v2
	v_or_b32_e32 v0, 0x7b, v0
	v_add_f32_e32 v2, 1.0, v2
	v_rcp_f32_e32 v2, v2
	s_nop 0
	v_mul_f32_e32 v2, v33, v2
	v_fma_mixlo_f16 v4, v17, v2, 0
	v_mad_i64_i32 v[2:3], s[12:13], v0, s2, v[130:131]
	global_store_short v[2:3], v4, off

; DI int TIDX() { int t = threadIdx.x; asm volatile("" : "+v"(t)); return t; }
; #define XCD_LOOP_W(Mt, ntn) const int xcd_ = BIDX() & 7; const int Mx_ = ((Mt) + 7) >> 3; for (int u_ = BIDX() >> 3; u_ < Mx_ * (ntn); u_ += (int)(gridDim.x >> 3))
; template <class BR>
; DI void gemm_tile_w(const h16* __restrict__ A, int lda, const h16* __restrict__ B, int ldb, BR brow, int K, f32x16 (&acc)[4][2], h16* sm) {
;   const int tid = TIDX(), lane = tid & 63, w = tid >> 6, wm = w >> 1, wn = w & 1, r = lane & 31, hh = lane >> 5;
;   const unsigned ao = (unsigned)(tid >> 2) * (unsigned)lda + (unsigned)(tid & 3) * 8u;
;   const unsigned bo0 = (unsigned)brow(tid >> 2) * (unsigned)ldb + (unsigned)(tid & 3) * 8u;
;   const unsigned bo1 = (unsigned)brow((tid >> 2) + 64) * (unsigned)ldb + (unsigned)(tid & 3) * 8u;
;   const h16* ag = A;
;   const h16* bg = B;
;   u32x4 ra0[4], rb0[2], ra1[4], rb1[2];
; #pragma unroll
;   for (int i = 0; i < 4; ++i) ra0[i] = *(const u32x4*)(ag + (ao + (unsigned)i * 64u * (unsigned)lda));
;   rb0[0] = *(const u32x4*)(bg + bo0);
;   rb0[1] = *(const u32x4*)(bg + bo1);
;   ag += 32; bg += 32;
; #pragma unroll
;   for (int i = 0; i < 4; ++i) ra1[i] = *(const u32x4*)(ag + (ao + (unsigned)i * 64u * (unsigned)lda));
;   rb1[0] = *(const u32x4*)(bg + bo0);
;   rb1[1] = *(const u32x4*)(bg + bo1);
;   const int nk = K >> 5;
;   const int wofs = (tid >> 2) * LS2 + (tid & 3) * 8;
; DI void phase_ffn1(const P& p, int l, int hf, char* smem) {
;     ...
;   XCD_LOOP_W(Mt, 44) {
;     int mt_, nt_;
;     tile_map(u_, Mx_, 44, xcd_, mt_, nt_);
;     if (mt_ >= Mt) continue;
;     const int m0 = mt0 * 128 + mt_ * 256, c0 = nt_ * 64;
;     f32x16 acc[4][2];
;     zero_acc_w(acc);
;     gemm_tile_w(h2 + (size_t)m0 * 1024, 1024, W, 1024,
;                 [&](int rr) { const int q = rr & 63; return ((q >> 5) ? 2816 : 0) + c0 + (rr >> 6) * 32 + (q & 31); }, 1024, acc, (h16*)smem);
.LBB0_71:
	s_mul_hi_i32 s12, s22, 0x2e8ba2e9
	s_lshr_b32 s13, s12, 31
	s_ashr_i32 s12, s12, 6
	s_add_i32 s12, s12, s13
	s_lshl_b32 s14, s12, 3
	s_sub_i32 s13, s21, s14
	s_min_i32 s15, s13, 8
	s_abs_i32 s13, s15
	v_cvt_f32_u32_e32 v0, s13
	s_sub_i32 s18, 0, s13
	s_mulk_i32 s12, 0xfea0
	s_add_i32 s12, s12, s22
	v_rcp_iflag_f32_e32 v0, v0
	s_abs_i32 s16, s12
	s_xor_b32 s17, s12, s15
	s_ashr_i32 s17, s17, 31
	v_mul_f32_e32 v0, 0x4f7ffffe, v0
	v_cvt_u32_f32_e32 v0, v0
	s_nop 0
	v_readfirstlane_b32 s19, v0
	s_mul_i32 s18, s18, s19
	s_mul_hi_u32 s18, s19, s18
	s_add_i32 s19, s19, s18
	s_mul_hi_u32 s18, s16, s19
	s_mul_i32 s19, s18, s13
	s_sub_i32 s16, s16, s19
	s_add_i32 s26, s18, 1
	s_sub_i32 s19, s16, s13
	s_cmp_ge_u32 s16, s13
	s_cselect_b32 s18, s26, s18
	s_cselect_b32 s16, s19, s16
	s_add_i32 s19, s18, 1
	s_cmp_ge_u32 s16, s13
	s_cselect_b32 s13, s19, s18
	s_xor_b32 s13, s13, s17
	s_sub_i32 s13, s13, s17
	s_add_i32 s14, s14, s38
	s_mul_i32 s15, s15, s13
	s_add_i32 s14, s14, s12
	s_sub_i32 s12, s14, s15
	s_cmp_ge_i32 s12, s20
	s_cbranch_scc1 .LBB0_70
	v_mov_b32_e32 v18, v203
	s_lshl_b32 s26, s13, 6
	s_lshl_b32 s12, s12, 8
	v_ashrrev_i32_e32 v19, 2, v18
	v_bfe_i32 v2, v18, 7, 1
	v_and_b32_e32 v2, 0xb00, v2
	v_lshrrev_b32_e32 v3, 3, v18
	v_and_or_b32 v4, v19, 31, s26
	v_and_b32_e32 v3, 0x3fffe0, v3
	v_add_u32_e32 v2, v2, v4
	v_add_u32_e32 v10, v2, v3
	v_add_u32_e32 v3, 64, v19
	s_ashr_i32 s13, s12, 31
	v_lshlrev_b32_e32 v0, 3, v18
	v_lshrrev_b32_e32 v3, 1, v3
	s_lshl_b64 s[14:15], s[12:13], 11
	v_and_b32_e32 v20, 24, v0
	v_bfe_u32 v21, v18, 4, 2
	v_lshlrev_b32_e32 v21, 3, v21
	v_xor_b32_e32 v20, v20, v21
	v_and_b32_e32 v3, 0x3fffe0, v3
	s_add_u32 s14, s24, s14
	v_add_u32_e32 v11, v2, v3
	v_lshl_or_b32 v210, v10, 10, v20
	v_mov_b32_e32 v211, v1
	s_addc_u32 s15, s25, s15
	v_lshl_or_b32 v0, v19, 10, v20
	v_lshl_or_b32 v212, v11, 10, v20
	v_lshlrev_b64 v[10:11], 1, v[210:211]
	v_mov_b32_e32 v213, v1
	v_lshl_add_u64 v[2:3], v[0:1], 1, s[14:15]
	v_add_u32_e32 v204, 0x10000, v0
	v_mov_b32_e32 v205, v1
	v_add_u32_e32 v206, 0x20000, v0
	v_mov_b32_e32 v207, v1
	v_add_u32_e32 v208, 0x30000, v0
	v_mov_b32_e32 v209, v1
	v_lshl_add_u64 v[12:13], s[6:7], 0, v[10:11]
	v_lshlrev_b64 v[14:15], 1, v[212:213]
	v_lshl_add_u64 v[4:5], v[204:205], 1, s[14:15]
	v_lshl_add_u64 v[6:7], v[206:207], 1, s[14:15]
	v_lshl_add_u64 v[8:9], v[208:209], 1, s[14:15]
	v_lshl_add_u64 v[16:17], s[6:7], 0, v[14:15]
	v_readfirstlane_b32 s18, v203
	s_nop 3
	s_lshr_b32 s18, s18, 6
	s_lshl_b32 s18, s18, 10
	v_and_b32_e32 v136, 31, v203
	v_bfe_u32 v137, v203, 5, 1
	v_bfe_u32 v138, v203, 2, 2
	v_xor_b32_e32 v137, v137, v138
	v_lshlrev_b32_e32 v137, 4, v137
	v_lshl_or_b32 v136, v136, 6, v137
	v_lshrrev_b32_e32 v138, 7, v203
	v_lshl_add_u32 v130, v138, 13, v136
	v_bfe_u32 v138, v203, 6, 1
	v_lshl_add_u32 v132, v138, 12, v136
	v_xor_b32_e32 v131, 32, v130
	v_xor_b32_e32 v133, 32, v132
	v_lshlrev_b32_e32 v139, 1, v0
	v_lshlrev_b32_e32 v140, 1, v204
	v_lshlrev_b32_e32 v141, 1, v206
	v_lshlrev_b32_e32 v142, 1, v208
	v_lshlrev_b32_e32 v143, 1, v210
	v_lshlrev_b32_e32 v144, 1, v212
	s_mov_b64 s[16:17], s[6:7]
	s_cmp_eq_u32 s39, 1
	s_cbranch_scc1 .Lfg_pfskip
	s_add_u32 m0, s18, 0x0
	s_nop 0
	global_load_lds_dwordx4 v139, s[14:15]
	s_add_u32 m0, s18, 0x1000
	s_nop 0
	global_load_lds_dwordx4 v140, s[14:15]
	s_add_u32 m0, s18, 0x2000
	s_nop 0
	global_load_lds_dwordx4 v141, s[14:15]
	s_add_u32 m0, s18, 0x3000
	s_nop 0
	global_load_lds_dwordx4 v142, s[14:15]
	s_add_u32 m0, s18, 0x4000
	s_nop 0
	global_load_lds_dwordx4 v143, s[16:17]
	s_add_u32 m0, s18, 0x5000
	s_nop 0
	global_load_lds_dwordx4 v144, s[16:17]
.Lfg_pfskip:
	s_add_u32 s14, s14, 64
	s_addc_u32 s15, s15, 0
	s_add_u32 s16, s16, 64
	s_addc_u32 s17, s17, 0
	s_mov_b32 s39, 0
	v_mov_b32_e32 v2, 0
	s_mov_b32 s13, 0
	v_mov_b32_e32 v3, v2
	v_mov_b32_e32 v4, v2
	v_mov_b32_e32 v5, v2
	v_mov_b32_e32 v6, v2
	v_mov_b32_e32 v7, v2
	v_mov_b32_e32 v8, v2
	v_mov_b32_e32 v9, v2
	v_mov_b32_e32 v10, v2
	v_mov_b32_e32 v11, v2
	v_mov_b32_e32 v12, v2
	v_mov_b32_e32 v13, v2
	v_mov_b32_e32 v14, v2
	v_mov_b32_e32 v15, v2
	v_mov_b32_e32 v16, v2
	v_mov_b32_e32 v17, v2
	v_mov_b32_e32 v18, v2
	v_mov_b32_e32 v19, v2
	v_mov_b32_e32 v20, v2
	v_mov_b32_e32 v21, v2
	v_mov_b32_e32 v22, v2
	v_mov_b32_e32 v23, v2
	v_mov_b32_e32 v24, v2
	v_mov_b32_e32 v25, v2
	v_mov_b32_e32 v26, v2
	v_mov_b32_e32 v27, v2
	v_mov_b32_e32 v28, v2
	v_mov_b32_e32 v29, v2
	v_mov_b32_e32 v30, v2
	v_mov_b32_e32 v31, v2
	v_mov_b32_e32 v32, v2
	v_mov_b32_e32 v33, v2
	v_mov_b32_e32 v34, v2
	v_mov_b32_e32 v35, v2
	v_mov_b32_e32 v36, v2
	v_mov_b32_e32 v37, v2
	v_mov_b32_e32 v38, v2
	v_mov_b32_e32 v39, v2
	v_mov_b32_e32 v40, v2
	v_mov_b32_e32 v41, v2
	v_mov_b32_e32 v42, v2
	v_mov_b32_e32 v43, v2
	v_mov_b32_e32 v44, v2
	v_mov_b32_e32 v45, v2
	v_mov_b32_e32 v46, v2
	v_mov_b32_e32 v47, v2
	v_mov_b32_e32 v48, v2
	v_mov_b32_e32 v49, v2
	s_waitcnt vmcnt(15)
	v_mov_b32_e32 v50, v2
	v_mov_b32_e32 v51, v2
	v_mov_b32_e32 v52, v2
	v_mov_b32_e32 v53, v2
	s_waitcnt vmcnt(14)
	v_mov_b32_e32 v54, v2
	v_mov_b32_e32 v55, v2
	v_mov_b32_e32 v56, v2
	v_mov_b32_e32 v57, v2
	s_waitcnt vmcnt(13)
	v_mov_b32_e32 v58, v2
	v_mov_b32_e32 v59, v2
	v_mov_b32_e32 v60, v2
	v_mov_b32_e32 v61, v2
	s_waitcnt vmcnt(12)
	v_mov_b32_e32 v62, v2
	v_mov_b32_e32 v63, v2
	v_mov_b32_e32 v64, v2
	v_mov_b32_e32 v65, v2
	v_mov_b32_e32 v66, v2
	v_mov_b32_e32 v67, v2
	v_mov_b32_e32 v68, v2
	v_mov_b32_e32 v69, v2
	v_mov_b32_e32 v70, v2
	v_mov_b32_e32 v71, v2
	v_mov_b32_e32 v72, v2
	v_mov_b32_e32 v73, v2
	v_mov_b32_e32 v74, v2
	v_mov_b32_e32 v75, v2
	v_mov_b32_e32 v76, v2
	v_mov_b32_e32 v77, v2
	v_mov_b32_e32 v78, v2
	v_mov_b32_e32 v79, v2
	v_mov_b32_e32 v80, v2
	v_mov_b32_e32 v81, v2
	v_mov_b32_e32 v82, v2
	v_mov_b32_e32 v83, v2
	v_mov_b32_e32 v84, v2
	v_mov_b32_e32 v85, v2
	v_mov_b32_e32 v86, v2
	v_mov_b32_e32 v87, v2
	v_mov_b32_e32 v88, v2
	v_mov_b32_e32 v89, v2
	v_mov_b32_e32 v90, v2
	v_mov_b32_e32 v91, v2
	v_mov_b32_e32 v92, v2
	v_mov_b32_e32 v93, v2
	v_mov_b32_e32 v94, v2
	v_mov_b32_e32 v95, v2
	v_mov_b32_e32 v96, v2
	v_mov_b32_e32 v97, v2
	v_mov_b32_e32 v98, v2
	v_mov_b32_e32 v99, v2
	v_mov_b32_e32 v100, v2
	v_mov_b32_e32 v101, v2
	v_mov_b32_e32 v102, v2
	v_mov_b32_e32 v103, v2
	v_mov_b32_e32 v104, v2
	v_mov_b32_e32 v105, v2
	v_mov_b32_e32 v106, v2
	v_mov_b32_e32 v107, v2
	v_mov_b32_e32 v108, v2
	v_mov_b32_e32 v109, v2
	v_mov_b32_e32 v110, v2
	v_mov_b32_e32 v111, v2
	v_mov_b32_e32 v112, v2
	v_mov_b32_e32 v113, v2
	v_mov_b32_e32 v114, v2
	v_mov_b32_e32 v115, v2
	v_mov_b32_e32 v116, v2
	v_mov_b32_e32 v117, v2
	v_mov_b32_e32 v118, v2
	v_mov_b32_e32 v119, v2
	v_mov_b32_e32 v120, v2
	v_mov_b32_e32 v121, v2
	v_mov_b32_e32 v122, v2
	v_mov_b32_e32 v123, v2
	v_mov_b32_e32 v124, v2
	v_mov_b32_e32 v125, v2
	v_mov_b32_e32 v126, v2
	v_mov_b32_e32 v127, v2
	v_mov_b32_e32 v128, v2
	v_mov_b32_e32 v129, v2
	s_waitcnt vmcnt(0)
	s_barrier
